# attention loops: common path straightened (rescale check, alpha check and end-of-PV barrier select fall through; rare blocks out of line)
# speedup vs baseline: 1.0080x; 1.0080x over previous
; __device__ __forceinline__ float softmax_rel(f32x16& p0, f32x16& p1, bool first, float& m_reg, float& l_reg, bf16x8& pa0, bf16x8& pa1, bf16x8& pa2, bf16x8& pa3) {
;     ...
;   if (__builtin_expect(first || __any(pmax > THR2), 0)) {
;     const float dl = first ? pmax : fmaxf(pmax, 0.f);
;     m_reg += dl; alpha = first ? 1.f : __builtin_amdgcn_exp2f(-dl);
; #pragma unroll
;     for (int r = 0; r < 16; ++r) { p0[r] -= dl; p1[r] -= dl; }
;   }
; #pragma unroll
;   for (int r = 0; r < 16; ++r) p0[r] = __builtin_amdgcn_exp2f(p0[r]);
; #pragma unroll
;   for (int r = 0; r < 16; ++r) p1[r] = __builtin_amdgcn_exp2f(p1[r]);
;   float ps = 0;
; #pragma unroll
;   for (int r = 0; r < 16; ++r) ps += p0[r];
; #pragma unroll
;   for (int r = 0; r < 16; ++r) ps += p1[r];
;   { auto rr = __builtin_amdgcn_permlane32_swap(__float_as_uint(ps), __float_as_uint(ps), false, false);
;     ps = __uint_as_float(rr[0]) + __uint_as_float(rr[1]); }
;   l_reg = l_reg * alpha + ps;
;   PK4(p0, 0, pa0); PK4(p0, 8, pa1); PK4(p1, 0, pa2); PK4(p1, 8, pa3);
.Lq0_nodma:
	s_waitcnt lgkmcnt(6)
	v_mfma_f32_32x32x16_bf16 v[144:159], v[230:233], v[184:187], v[144:159]
	v_mfma_f32_32x32x16_bf16 v[128:143], v[234:237], v[184:187], v[128:143]
	v_xor_b32_e32 v220, 0xa0, v213
	v_add_u32_e32 v220, v212, v220
	ds_read_b128 v[230:233], v220 offset:0
	ds_read_b128 v[234:237], v220 offset:0x2000
	s_waitcnt lgkmcnt(6)
	v_mfma_f32_32x32x16_bf16 v[144:159], v[238:241], v[180:183], v[144:159]
	v_mfma_f32_32x32x16_bf16 v[128:143], v[242:245], v[180:183], v[128:143]
	v_xor_b32_e32 v220, 0xc0, v213
	v_add_u32_e32 v220, v212, v220
	ds_read_b128 v[238:241], v220 offset:0
	ds_read_b128 v[242:245], v220 offset:0x2000
	s_waitcnt lgkmcnt(6)
	v_mfma_f32_32x32x16_bf16 v[144:159], v[246:249], v[176:179], v[144:159]
	v_mfma_f32_32x32x16_bf16 v[128:143], v[214:217], v[176:179], v[128:143]
	v_xor_b32_e32 v214, 0xe0, v213
	v_add_u32_e32 v212, v212, v214
	ds_read_b128 v[214:217], v212 offset:0
	ds_read_b128 v[246:249], v212 offset:0x2000
	s_waitcnt lgkmcnt(6)
	v_mfma_f32_32x32x16_bf16 v[144:159], v[194:197], v[172:175], v[144:159]
	v_mfma_f32_32x32x16_bf16 v[128:143], v[226:229], v[172:175], v[128:143]
	s_waitcnt lgkmcnt(4)
	v_mfma_f32_32x32x16_bf16 v[144:159], v[230:233], v[168:171], v[144:159]
	v_mfma_f32_32x32x16_bf16 v[128:143], v[234:237], v[168:171], v[128:143]
	s_waitcnt lgkmcnt(2)
	v_mfma_f32_32x32x16_bf16 v[144:159], v[238:241], v[164:167], v[144:159]
	v_mfma_f32_32x32x16_bf16 v[128:143], v[242:245], v[164:167], v[128:143]
	s_waitcnt lgkmcnt(0)
	v_mfma_f32_32x32x16_bf16 v[144:159], v[214:217], v[160:163], v[144:159]
	s_cmp_eq_u32 s10, 0
	s_cselect_b64 s[62:63], -1, 0
	s_cmp_lg_u32 s10, 0
	v_mfma_f32_32x32x16_bf16 v[128:143], v[246:249], v[160:163], v[128:143]
	s_nop 7
	v_max_f32_e32 v194, v145, v145
	v_max_f32_e32 v195, v144, v144
	v_max_f32_e32 v194, v195, v194
	v_max3_f32 v194, v194, v146, v147
	v_max3_f32 v194, v194, v148, v149
	v_max3_f32 v195, v128, v129, v130
	v_max3_f32 v194, v194, v150, v151
	v_max3_f32 v195, v195, v131, v132
	v_max3_f32 v194, v194, v152, v153
	v_max3_f32 v195, v195, v133, v134
	v_max3_f32 v194, v194, v154, v155
	v_max3_f32 v195, v195, v135, v136
	v_max3_f32 v194, v194, v156, v157
	v_max3_f32 v195, v195, v137, v138
	v_max3_f32 v194, v194, v158, v159
	v_max3_f32 v195, v195, v139, v140
	v_max3_f32 v195, v195, v141, v142
	v_max3_f32 v194, v194, v195, v143
	v_mov_b32_e32 v195, v194
	s_nop 1
	v_permlane32_swap_b32_e32 v194, v195
	v_max_f32_e32 v195, v195, v195
	v_max_f32_e32 v194, v194, v194
	v_max_f32_e32 v226, v194, v195
	s_cbranch_scc0 .LBB0_371
	v_cmp_lt_f32_e32 vcc, s30, v226
	s_cbranch_vccnz .Lm0_rare
	v_mov_b32_e32 v226, 1.0
.LBB0_355:
	v_exp_f32_e32 v144, v144
	v_exp_f32_e32 v145, v145
	v_exp_f32_e32 v146, v146
	v_exp_f32_e32 v147, v147
	v_exp_f32_e32 v148, v148
	v_exp_f32_e32 v194, v128
	v_add_f32_e32 v128, 0, v144
	v_exp_f32_e32 v149, v149
	v_add_f32_e32 v128, v145, v128
	v_exp_f32_e32 v150, v150
	v_add_f32_e32 v128, v146, v128
	v_exp_f32_e32 v151, v151
	v_add_f32_e32 v128, v147, v128
	v_exp_f32_e32 v152, v152
	v_add_f32_e32 v128, v148, v128
	v_exp_f32_e32 v153, v153
	v_add_f32_e32 v128, v149, v128
	v_exp_f32_e32 v154, v154
	v_add_f32_e32 v128, v150, v128
	v_exp_f32_e32 v155, v155
	v_add_f32_e32 v128, v151, v128
	v_exp_f32_e32 v156, v156
	v_add_f32_e32 v128, v152, v128
	v_exp_f32_e32 v157, v157
	v_add_f32_e32 v128, v153, v128
	v_exp_f32_e32 v158, v158
	v_add_f32_e32 v128, v154, v128
	v_exp_f32_e32 v159, v159
	v_add_f32_e32 v128, v155, v128
	v_add_f32_e32 v128, v156, v128
	v_exp_f32_e32 v195, v129
	v_add_f32_e32 v128, v157, v128
	v_exp_f32_e32 v196, v130
	v_add_f32_e32 v128, v158, v128
	v_exp_f32_e32 v197, v131
	v_add_f32_e32 v128, v159, v128
	v_exp_f32_e32 v214, v132
	v_add_f32_e32 v128, v194, v128
	v_exp_f32_e32 v215, v133
	v_add_f32_e32 v128, v195, v128
	v_exp_f32_e32 v216, v134
	v_add_f32_e32 v128, v196, v128
	v_exp_f32_e32 v217, v135
	v_add_f32_e32 v128, v197, v128
	v_exp_f32_e32 v220, v136
	v_add_f32_e32 v128, v214, v128
	v_exp_f32_e32 v221, v137
	v_add_f32_e32 v128, v215, v128
	v_exp_f32_e32 v222, v138
	v_add_f32_e32 v128, v216, v128
	v_exp_f32_e32 v228, v139
	v_add_f32_e32 v128, v217, v128
	v_exp_f32_e32 v229, v140
	v_add_f32_e32 v128, v220, v128
	v_exp_f32_e32 v230, v141
	v_add_f32_e32 v128, v221, v128
	v_exp_f32_e32 v231, v142
	v_add_f32_e32 v128, v222, v128
	v_exp_f32_e32 v143, v143
	v_add_f32_e32 v128, v228, v128
	v_add_f32_e32 v128, v229, v128
	v_add_f32_e32 v128, v230, v128
	v_add_f32_e32 v128, v231, v128
	v_add_f32_e32 v212, v143, v128
	v_mov_b32_e32 v227, v212
	v_cvt_pk_bf16_f32 v128, v144, v145
	v_cvt_pk_bf16_f32 v129, v146, v147
	v_cvt_pk_bf16_f32 v130, v148, v149
	v_cvt_pk_bf16_f32 v131, v150, v151
	v_cvt_pk_bf16_f32 v132, v152, v153
	v_cvt_pk_bf16_f32 v133, v154, v155
	v_cvt_pk_bf16_f32 v134, v156, v157
	v_cvt_pk_bf16_f32 v135, v158, v159
	v_cvt_pk_bf16_f32 v136, v194, v195
	v_cvt_pk_bf16_f32 v137, v196, v197
	v_cvt_pk_bf16_f32 v138, v214, v215
	v_cvt_pk_bf16_f32 v139, v216, v217
	v_cvt_pk_bf16_f32 v140, v220, v221
	v_cvt_pk_bf16_f32 v141, v222, v228
	v_cvt_pk_bf16_f32 v142, v229, v230
	v_cvt_pk_bf16_f32 v143, v231, v143
	s_nop 1
	v_permlane32_swap_b32_e32 v212, v227
	v_cmp_gt_f32_e32 vcc, 1.0, v226
	s_cbranch_vccnz .Lm0_resc

; #define SBAR() __builtin_amdgcn_sched_barrier(0)
; #define VF_WAIT(N) do { asm volatile("s_waitcnt lgkmcnt(" #N ")" ::: "memory"); SBAR(); } while (0)
; #define A_WAITBAR(N) asm volatile("s_waitcnt vmcnt(" #N ") lgkmcnt(0) ; A256BAR\n\ts_barrier" ::: "memory")
; __device__ __forceinline__ void pv8(f32x16* o, int vb, bf16x8 pa0, bf16x8 pa1, bf16x8 pa2, bf16x8 pa3) {
;   VFrag fa, fb; const int vb2 = vb + 16384;
;   vf_read<0>(fa, vb);
;   vf_read<1>(fb, vb);  VF_WAIT(8); vf_mma(o[0], fa, pa0, pa1, pa2, pa3); SBAR();
;   vf_read<2>(fa, vb);  VF_WAIT(8); vf_mma(o[1], fb, pa0, pa1, pa2, pa3); SBAR();
;   vf_read<3>(fb, vb);  VF_WAIT(8); vf_mma(o[2], fa, pa0, pa1, pa2, pa3); SBAR();
;   vf_read<0>(fa, vb2); VF_WAIT(8); vf_mma(o[3], fb, pa0, pa1, pa2, pa3); SBAR();
;   vf_read<1>(fb, vb2); VF_WAIT(8); vf_mma(o[4], fa, pa0, pa1, pa2, pa3); SBAR();
;   vf_read<2>(fa, vb2); VF_WAIT(8); vf_mma(o[5], fb, pa0, pa1, pa2, pa3); SBAR();
;   vf_read<3>(fb, vb2); VF_WAIT(8); vf_mma(o[6], fa, pa0, pa1, pa2, pa3); SBAR();
;   VF_WAIT(0); vf_mma(o[7], fb, pa0, pa1, pa2, pa3);
; }
; template <int mode> ...
;     ...
;     if (more) A_WAITBAR(6); else A_WAITBAR(0);
.Lp0_nodma:
	s_waitcnt lgkmcnt(8)
	v_mfma_f32_32x32x16_bf16 v[96:111], v[128:131], v[194:197], v[96:111]
	v_mfma_f32_32x32x16_bf16 v[96:111], v[132:135], v[214:217], v[96:111]
	v_mfma_f32_32x32x16_bf16 v[96:111], v[136:139], v[228:231], v[96:111]
	v_mfma_f32_32x32x16_bf16 v[96:111], v[140:143], v[232:235], v[96:111]
	ds_read_b64_tr_b16 v[194:195], v220 offset:0x600
	ds_read_b64_tr_b16 v[196:197], v220 offset:0xe00
	ds_read_b64_tr_b16 v[214:215], v220 offset:0x1600
	ds_read_b64_tr_b16 v[216:217], v220 offset:0x1e00
	ds_read_b64_tr_b16 v[228:229], v220 offset:0x2600
	ds_read_b64_tr_b16 v[230:231], v220 offset:0x2e00
	ds_read_b64_tr_b16 v[232:233], v220 offset:0x3600
	ds_read_b64_tr_b16 v[234:235], v220 offset:0x3e00
	s_waitcnt lgkmcnt(8)
	v_mfma_f32_32x32x16_bf16 v[80:95], v[128:131], v[144:147], v[80:95]
	v_mfma_f32_32x32x16_bf16 v[80:95], v[132:135], v[148:151], v[80:95]
	v_mfma_f32_32x32x16_bf16 v[80:95], v[136:139], v[152:155], v[80:95]
	v_mfma_f32_32x32x16_bf16 v[80:95], v[140:143], v[156:159], v[80:95]
	ds_read_b64_tr_b16 v[144:145], v221 offset:0
	ds_read_b64_tr_b16 v[146:147], v221 offset:0x800
	ds_read_b64_tr_b16 v[148:149], v221 offset:0x1000
	ds_read_b64_tr_b16 v[150:151], v221 offset:0x1800
	ds_read_b64_tr_b16 v[152:153], v221 offset:0x2000
	ds_read_b64_tr_b16 v[154:155], v221 offset:0x2800
	ds_read_b64_tr_b16 v[156:157], v221 offset:0x3000
	ds_read_b64_tr_b16 v[158:159], v221 offset:0x3800
	s_waitcnt lgkmcnt(8)
	v_mfma_f32_32x32x16_bf16 v[64:79], v[128:131], v[194:197], v[64:79]
	v_mfma_f32_32x32x16_bf16 v[64:79], v[132:135], v[214:217], v[64:79]
	v_mfma_f32_32x32x16_bf16 v[64:79], v[136:139], v[228:231], v[64:79]
	v_mfma_f32_32x32x16_bf16 v[64:79], v[140:143], v[232:235], v[64:79]
	ds_read_b64_tr_b16 v[194:195], v221 offset:0x200
	ds_read_b64_tr_b16 v[196:197], v221 offset:0xa00
	ds_read_b64_tr_b16 v[214:215], v221 offset:0x1200
	ds_read_b64_tr_b16 v[216:217], v221 offset:0x1a00
	ds_read_b64_tr_b16 v[228:229], v221 offset:0x2200
	ds_read_b64_tr_b16 v[230:231], v221 offset:0x2a00
	ds_read_b64_tr_b16 v[232:233], v221 offset:0x3200
	ds_read_b64_tr_b16 v[234:235], v221 offset:0x3a00
	s_waitcnt lgkmcnt(8)
	v_mfma_f32_32x32x16_bf16 v[48:63], v[128:131], v[144:147], v[48:63]
	v_mfma_f32_32x32x16_bf16 v[48:63], v[132:135], v[148:151], v[48:63]
	v_mfma_f32_32x32x16_bf16 v[48:63], v[136:139], v[152:155], v[48:63]
	v_mfma_f32_32x32x16_bf16 v[48:63], v[140:143], v[156:159], v[48:63]
	ds_read_b64_tr_b16 v[144:145], v221 offset:0x400
	ds_read_b64_tr_b16 v[146:147], v221 offset:0xc00
	ds_read_b64_tr_b16 v[148:149], v221 offset:0x1400
	ds_read_b64_tr_b16 v[150:151], v221 offset:0x1c00
	ds_read_b64_tr_b16 v[152:153], v221 offset:0x2400
	ds_read_b64_tr_b16 v[154:155], v221 offset:0x2c00
	ds_read_b64_tr_b16 v[156:157], v221 offset:0x3400
	ds_read_b64_tr_b16 v[158:159], v221 offset:0x3c00
	s_waitcnt lgkmcnt(8)
	v_mfma_f32_32x32x16_bf16 v[32:47], v[128:131], v[194:197], v[32:47]
	v_mfma_f32_32x32x16_bf16 v[32:47], v[132:135], v[214:217], v[32:47]
	v_mfma_f32_32x32x16_bf16 v[32:47], v[136:139], v[228:231], v[32:47]
	v_mfma_f32_32x32x16_bf16 v[32:47], v[140:143], v[232:235], v[32:47]
	ds_read_b64_tr_b16 v[194:195], v221 offset:0x600
	ds_read_b64_tr_b16 v[196:197], v221 offset:0xe00
	ds_read_b64_tr_b16 v[214:215], v221 offset:0x1600
	ds_read_b64_tr_b16 v[216:217], v221 offset:0x1e00
	ds_read_b64_tr_b16 v[228:229], v221 offset:0x2600
	ds_read_b64_tr_b16 v[230:231], v221 offset:0x2e00
	ds_read_b64_tr_b16 v[232:233], v221 offset:0x3600
	ds_read_b64_tr_b16 v[234:235], v221 offset:0x3e00
	s_waitcnt lgkmcnt(8)
	v_mfma_f32_32x32x16_bf16 v[16:31], v[128:131], v[144:147], v[16:31]
	v_mfma_f32_32x32x16_bf16 v[16:31], v[132:135], v[148:151], v[16:31]
	v_mfma_f32_32x32x16_bf16 v[16:31], v[136:139], v[152:155], v[16:31]
	v_mfma_f32_32x32x16_bf16 v[16:31], v[140:143], v[156:159], v[16:31]
	s_waitcnt lgkmcnt(0)
	v_mfma_f32_32x32x16_bf16 v[0:15], v[128:131], v[194:197], v[0:15]
	s_and_b64 vcc, exec, s[90:91]
	v_mfma_f32_32x32x16_bf16 v[0:15], v[132:135], v[214:217], v[0:15]
	v_mfma_f32_32x32x16_bf16 v[0:15], v[136:139], v[228:231], v[0:15]
	v_mfma_f32_32x32x16_bf16 v[0:15], v[140:143], v[232:235], v[0:15]
	s_cbranch_vccnz .Lm0_ybar0
	s_waitcnt vmcnt(6) lgkmcnt(0)
	s_barrier

; __device__ __forceinline__ float softmax_rel(f32x16& p0, f32x16& p1, bool first, float& m_reg, float& l_reg, bf16x8& pa0, bf16x8& pa1, bf16x8& pa2, bf16x8& pa3) {
;     ...
;   if (__builtin_expect(first || __any(pmax > THR2), 0)) {
;     const float dl = first ? pmax : fmaxf(pmax, 0.f);
;     m_reg += dl; alpha = first ? 1.f : __builtin_amdgcn_exp2f(-dl);
.Lm0_rare:
	s_mov_b64 s[24:25], 0
	s_mov_b64 s[96:97], 0
	s_branch .LBB0_372

; __device__ __forceinline__ float softmax_rel(f32x16& p0, f32x16& p1, bool first, float& m_reg, float& l_reg, bf16x8& pa0, bf16x8& pa1, bf16x8& pa2, bf16x8& pa3) {
;     ...
;   if (__builtin_expect(first || __any(pmax > THR2), 0)) {
;     const float dl = first ? pmax : fmaxf(pmax, 0.f);
;     m_reg += dl; alpha = first ? 1.f : __builtin_amdgcn_exp2f(-dl);
; #pragma unroll
;     for (int r = 0; r < 16; ++r) { p0[r] -= dl; p1[r] -= dl; }
;   }
.LBB0_354:
	v_exp_f32_e64 v194, -v212
	v_add_f32_e32 v224, v224, v212
	v_pk_add_f32 v[144:145], v[144:145], v[212:213] op_sel_hi:[1,0] neg_lo:[0,1] neg_hi:[0,1]
	v_pk_add_f32 v[128:129], v[128:129], v[212:213] op_sel_hi:[1,0] neg_lo:[0,1] neg_hi:[0,1]
	v_pk_add_f32 v[146:147], v[146:147], v[212:213] op_sel_hi:[1,0] neg_lo:[0,1] neg_hi:[0,1]
	v_pk_add_f32 v[130:131], v[130:131], v[212:213] op_sel_hi:[1,0] neg_lo:[0,1] neg_hi:[0,1]
	v_pk_add_f32 v[148:149], v[148:149], v[212:213] op_sel_hi:[1,0] neg_lo:[0,1] neg_hi:[0,1]
	v_pk_add_f32 v[132:133], v[132:133], v[212:213] op_sel_hi:[1,0] neg_lo:[0,1] neg_hi:[0,1]
	v_pk_add_f32 v[150:151], v[150:151], v[212:213] op_sel_hi:[1,0] neg_lo:[0,1] neg_hi:[0,1]
	v_pk_add_f32 v[134:135], v[134:135], v[212:213] op_sel_hi:[1,0] neg_lo:[0,1] neg_hi:[0,1]
	v_pk_add_f32 v[152:153], v[152:153], v[212:213] op_sel_hi:[1,0] neg_lo:[0,1] neg_hi:[0,1]
	v_pk_add_f32 v[136:137], v[136:137], v[212:213] op_sel_hi:[1,0] neg_lo:[0,1] neg_hi:[0,1]
	v_pk_add_f32 v[154:155], v[154:155], v[212:213] op_sel_hi:[1,0] neg_lo:[0,1] neg_hi:[0,1]
	v_pk_add_f32 v[138:139], v[138:139], v[212:213] op_sel_hi:[1,0] neg_lo:[0,1] neg_hi:[0,1]
	v_pk_add_f32 v[156:157], v[156:157], v[212:213] op_sel_hi:[1,0] neg_lo:[0,1] neg_hi:[0,1]
	v_pk_add_f32 v[140:141], v[140:141], v[212:213] op_sel_hi:[1,0] neg_lo:[0,1] neg_hi:[0,1]
	v_pk_add_f32 v[158:159], v[158:159], v[212:213] op_sel_hi:[1,0] neg_lo:[0,1] neg_hi:[0,1]
	v_pk_add_f32 v[142:143], v[142:143], v[212:213] op_sel_hi:[1,0] neg_lo:[0,1] neg_hi:[0,1]
	v_cndmask_b32_e64 v226, v194, 1.0, s[62:63]
	s_branch .LBB0_355
.Lm0_resc:
	s_and_saveexec_b64 s[24:25], s[40:41]
	ds_write_b32 v201, v226 offset:128
	s_or_b64 exec, exec, s[24:25]
	s_waitcnt lgkmcnt(0)
	v_add_u32_e32 v144, s8, v198
	ds_read_b128 v[156:159], v144 offset:224
	ds_read_b128 v[152:155], v144 offset:192
	ds_read_b128 v[148:151], v144 offset:160
	ds_read_b128 v[144:147], v144 offset:128
	s_waitcnt lgkmcnt(3)
	v_pk_mul_f32 v[124:125], v[124:125], v[156:157]
	s_waitcnt lgkmcnt(2)
	v_pk_mul_f32 v[120:121], v[120:121], v[152:153]
	s_waitcnt lgkmcnt(1)
	v_pk_mul_f32 v[116:117], v[116:117], v[148:149]
	v_pk_mul_f32 v[126:127], v[126:127], v[158:159]
	v_pk_mul_f32 v[122:123], v[122:123], v[154:155]
	v_pk_mul_f32 v[118:119], v[118:119], v[150:151]
	s_waitcnt lgkmcnt(0)
	v_pk_mul_f32 v[114:115], v[114:115], v[146:147]
	v_pk_mul_f32 v[112:113], v[112:113], v[144:145]
	v_pk_mul_f32 v[108:109], v[108:109], v[156:157]
	v_pk_mul_f32 v[104:105], v[104:105], v[152:153]
	v_pk_mul_f32 v[100:101], v[100:101], v[148:149]
	v_pk_mul_f32 v[110:111], v[110:111], v[158:159]
	v_pk_mul_f32 v[106:107], v[106:107], v[154:155]
	v_pk_mul_f32 v[102:103], v[102:103], v[150:151]
	v_pk_mul_f32 v[98:99], v[98:99], v[146:147]
	v_pk_mul_f32 v[96:97], v[96:97], v[144:145]
	v_pk_mul_f32 v[92:93], v[92:93], v[156:157]
	v_pk_mul_f32 v[88:89], v[88:89], v[152:153]
	v_pk_mul_f32 v[84:85], v[84:85], v[148:149]
	v_pk_mul_f32 v[94:95], v[94:95], v[158:159]
	v_pk_mul_f32 v[90:91], v[90:91], v[154:155]
	v_pk_mul_f32 v[86:87], v[86:87], v[150:151]
	v_pk_mul_f32 v[82:83], v[82:83], v[146:147]
	v_pk_mul_f32 v[80:81], v[80:81], v[144:145]
	v_pk_mul_f32 v[76:77], v[76:77], v[156:157]
	v_pk_mul_f32 v[72:73], v[72:73], v[152:153]
	v_pk_mul_f32 v[68:69], v[68:69], v[148:149]
	v_pk_mul_f32 v[78:79], v[78:79], v[158:159]
	v_pk_mul_f32 v[74:75], v[74:75], v[154:155]
	v_pk_mul_f32 v[70:71], v[70:71], v[150:151]
	v_pk_mul_f32 v[66:67], v[66:67], v[146:147]
	v_pk_mul_f32 v[64:65], v[64:65], v[144:145]
	v_pk_mul_f32 v[60:61], v[60:61], v[156:157]
	v_pk_mul_f32 v[56:57], v[56:57], v[152:153]
	v_pk_mul_f32 v[52:53], v[52:53], v[148:149]
	v_pk_mul_f32 v[62:63], v[62:63], v[158:159]
	v_pk_mul_f32 v[58:59], v[58:59], v[154:155]
	v_pk_mul_f32 v[54:55], v[54:55], v[150:151]
	v_pk_mul_f32 v[50:51], v[50:51], v[146:147]
	v_pk_mul_f32 v[48:49], v[48:49], v[144:145]
	v_pk_mul_f32 v[44:45], v[44:45], v[156:157]
	v_pk_mul_f32 v[40:41], v[40:41], v[152:153]
	v_pk_mul_f32 v[36:37], v[36:37], v[148:149]
	v_pk_mul_f32 v[46:47], v[46:47], v[158:159]
	v_pk_mul_f32 v[42:43], v[42:43], v[154:155]
	v_pk_mul_f32 v[38:39], v[38:39], v[150:151]
	v_pk_mul_f32 v[34:35], v[34:35], v[146:147]
	v_pk_mul_f32 v[32:33], v[32:33], v[144:145]
	v_pk_mul_f32 v[28:29], v[28:29], v[156:157]
	v_pk_mul_f32 v[24:25], v[24:25], v[152:153]
	v_pk_mul_f32 v[20:21], v[20:21], v[148:149]
	v_pk_mul_f32 v[30:31], v[30:31], v[158:159]
	v_pk_mul_f32 v[26:27], v[26:27], v[154:155]
	v_pk_mul_f32 v[22:23], v[22:23], v[150:151]
	v_pk_mul_f32 v[18:19], v[18:19], v[146:147]
	v_pk_mul_f32 v[16:17], v[16:17], v[144:145]
	v_pk_mul_f32 v[12:13], v[12:13], v[156:157]
	v_pk_mul_f32 v[8:9], v[8:9], v[152:153]
	v_pk_mul_f32 v[4:5], v[4:5], v[148:149]
	v_pk_mul_f32 v[14:15], v[14:15], v[158:159]
	v_pk_mul_f32 v[10:11], v[10:11], v[154:155]
	v_pk_mul_f32 v[6:7], v[6:7], v[150:151]
	v_pk_mul_f32 v[2:3], v[2:3], v[146:147]
	v_pk_mul_f32 v[0:1], v[0:1], v[144:145]
	s_branch .LBB0_359

; #define SBAR() __builtin_amdgcn_sched_barrier(0)
; #define KW(N) do { asm volatile("s_waitcnt lgkmcnt(" #N ")" ::: "memory"); SBAR(); } while (0)
; __device__ __forceinline__ float softmax_rel(f32x16& p0, f32x16& p1, bool first, float& m_reg, float& l_reg, bf16x8& pa0, bf16x8& pa1, bf16x8& pa2, bf16x8& pa3) {
;   float pmax = p0[0];
; #pragma unroll
;   for (int r = 1; r < 16; ++r) pmax = fmaxf(pmax, p0[r]);
; #pragma unroll
;   for (int r = 0; r < 16; ++r) pmax = fmaxf(pmax, p1[r]);
;   { auto rr = __builtin_amdgcn_permlane32_swap(__float_as_uint(pmax), __float_as_uint(pmax), false, false);
;     pmax = fmaxf(__uint_as_float(rr[0]), __uint_as_float(rr[1])); }
;   float alpha = 1.f;
;   if (__builtin_expect(first || __any(pmax > THR2), 0)) {
;     const float dl = first ? pmax : fmaxf(pmax, 0.f);
;     m_reg += dl; alpha = first ? 1.f : __builtin_amdgcn_exp2f(-dl);
; #pragma unroll
;     for (int r = 0; r < 16; ++r) { p0[r] -= dl; p1[r] -= dl; }
;   }
; #pragma unroll
;   for (int r = 0; r < 16; ++r) p0[r] = __builtin_amdgcn_exp2f(p0[r]);
; #pragma unroll
;   for (int r = 0; r < 16; ++r) p1[r] = __builtin_amdgcn_exp2f(p1[r]);
;   float ps = 0;
; #pragma unroll
;   for (int r = 0; r < 16; ++r) ps += p0[r];
; #pragma unroll
;   for (int r = 0; r < 16; ++r) ps += p1[r];
;   { auto rr = __builtin_amdgcn_permlane32_swap(__float_as_uint(ps), __float_as_uint(ps), false, false);
;     ps = __uint_as_float(rr[0]) + __uint_as_float(rr[1]); }
;   l_reg = l_reg * alpha + ps;
;   PK4(p0, 0, pa0); PK4(p0, 8, pa1); PK4(p1, 0, pa2); PK4(p1, 8, pa3);
; __device__ __forceinline__ void qkt_pipe(f32x16& p0, f32x16& p1, int kbt, int kc, const bf16x8* qr, const f32x16& z) {
;     ...
;   KW(6); p0 = __builtin_amdgcn_mfma_f32_32x32x16_bf16(a0, qr[4], p0, 0, 0, 0); p1 = __builtin_amdgcn_mfma_f32_32x32x16_bf16(b0, qr[4], p1, 0, 0, 0); SBAR();
;   KW(4); p0 = __builtin_amdgcn_mfma_f32_32x32x16_bf16(a1, qr[5], p0, 0, 0, 0); p1 = __builtin_amdgcn_mfma_f32_32x32x16_bf16(b1, qr[5], p1, 0, 0, 0); SBAR();
;   KW(2); p0 = __builtin_amdgcn_mfma_f32_32x32x16_bf16(a2, qr[6], p0, 0, 0, 0); p1 = __builtin_amdgcn_mfma_f32_32x32x16_bf16(b2, qr[6], p1, 0, 0, 0); SBAR();
;   KW(0); p0 = __builtin_amdgcn_mfma_f32_32x32x16_bf16(a3, qr[7], p0, 0, 0, 0); p1 = __builtin_amdgcn_mfma_f32_32x32x16_bf16(b3, qr[7], p1, 0, 0, 0);
.Lq1_nodma:
	s_waitcnt lgkmcnt(6)
	v_mfma_f32_32x32x16_bf16 v[144:159], v[230:233], v[184:187], v[144:159]
	v_mfma_f32_32x32x16_bf16 v[128:143], v[234:237], v[184:187], v[128:143]
	v_xor_b32_e32 v229, 0xa0, v225
	v_add_u32_e32 v229, v212, v229
	ds_read_b128 v[230:233], v229 offset:0
	ds_read_b128 v[234:237], v229 offset:0x2000
	s_waitcnt lgkmcnt(6)
	v_mfma_f32_32x32x16_bf16 v[144:159], v[238:241], v[180:183], v[144:159]
	v_mfma_f32_32x32x16_bf16 v[128:143], v[242:245], v[180:183], v[128:143]
	v_xor_b32_e32 v229, 0xc0, v225
	v_add_u32_e32 v229, v212, v229
	ds_read_b128 v[238:241], v229 offset:0
	ds_read_b128 v[242:245], v229 offset:0x2000
	s_waitcnt lgkmcnt(6)
	v_mfma_f32_32x32x16_bf16 v[144:159], v[246:249], v[176:179], v[144:159]
	v_mfma_f32_32x32x16_bf16 v[128:143], v[220:223], v[176:179], v[128:143]
	v_xor_b32_e32 v220, 0xe0, v225
	v_add_u32_e32 v212, v212, v220
	ds_read_b128 v[220:223], v212 offset:0
	ds_read_b128 v[246:249], v212 offset:0x2000
	s_waitcnt lgkmcnt(6)
	v_mfma_f32_32x32x16_bf16 v[144:159], v[194:197], v[172:175], v[144:159]
	v_mfma_f32_32x32x16_bf16 v[128:143], v[214:217], v[172:175], v[128:143]
	s_waitcnt lgkmcnt(4)
	v_mfma_f32_32x32x16_bf16 v[144:159], v[230:233], v[168:171], v[144:159]
	v_mfma_f32_32x32x16_bf16 v[128:143], v[234:237], v[168:171], v[128:143]
	s_waitcnt lgkmcnt(2)
	v_mfma_f32_32x32x16_bf16 v[144:159], v[238:241], v[164:167], v[144:159]
	v_mfma_f32_32x32x16_bf16 v[128:143], v[242:245], v[164:167], v[128:143]
	s_waitcnt lgkmcnt(0)
	v_mfma_f32_32x32x16_bf16 v[144:159], v[220:223], v[160:163], v[144:159]
	s_cmp_eq_u32 s9, 0
	s_cselect_b64 s[56:57], -1, 0
	s_cmp_lg_u32 s9, 0
	v_mfma_f32_32x32x16_bf16 v[128:143], v[246:249], v[160:163], v[128:143]
	s_nop 7
	v_max_f32_e32 v194, v145, v145
	v_max_f32_e32 v195, v144, v144
	v_max_f32_e32 v194, v195, v194
	v_max3_f32 v194, v194, v146, v147
	v_max3_f32 v194, v194, v148, v149
	v_max3_f32 v195, v128, v129, v130
	v_max3_f32 v194, v194, v150, v151
	v_max3_f32 v195, v195, v131, v132
	v_max3_f32 v194, v194, v152, v153
	v_max3_f32 v195, v195, v133, v134
	v_max3_f32 v194, v194, v154, v155
	v_max3_f32 v195, v195, v135, v136
	v_max3_f32 v194, v194, v156, v157
	v_max3_f32 v195, v195, v137, v138
	v_max3_f32 v194, v194, v158, v159
	v_max3_f32 v195, v195, v139, v140
	v_max3_f32 v195, v195, v141, v142
	v_max3_f32 v194, v194, v195, v143
	v_mov_b32_e32 v195, v194
	s_nop 1
	v_permlane32_swap_b32_e32 v194, v195
	v_max_f32_e32 v195, v195, v195
	v_max_f32_e32 v194, v194, v194
	v_max_f32_e32 v229, v194, v195
	s_cbranch_scc0 .LBB0_404
	v_cmp_lt_f32_e32 vcc, s30, v229
	s_cbranch_vccnz .Lm1_rare
	v_mov_b32_e32 v229, 1.0
.LBB0_388:
	v_exp_f32_e32 v144, v144
	v_exp_f32_e32 v145, v145
	v_exp_f32_e32 v146, v146
	v_exp_f32_e32 v147, v147
	v_exp_f32_e32 v148, v148
	v_exp_f32_e32 v194, v128
	v_add_f32_e32 v128, 0, v144
	v_exp_f32_e32 v149, v149
	v_add_f32_e32 v128, v145, v128
	v_exp_f32_e32 v150, v150
	v_add_f32_e32 v128, v146, v128
	v_exp_f32_e32 v151, v151
	v_add_f32_e32 v128, v147, v128
	v_exp_f32_e32 v152, v152
	v_add_f32_e32 v128, v148, v128
	v_exp_f32_e32 v153, v153
	v_add_f32_e32 v128, v149, v128
	v_exp_f32_e32 v154, v154
	v_add_f32_e32 v128, v150, v128
	v_exp_f32_e32 v155, v155
	v_add_f32_e32 v128, v151, v128
	v_exp_f32_e32 v156, v156
	v_add_f32_e32 v128, v152, v128
	v_exp_f32_e32 v157, v157
	v_add_f32_e32 v128, v153, v128
	v_exp_f32_e32 v158, v158
	v_add_f32_e32 v128, v154, v128
	v_exp_f32_e32 v159, v159
	v_add_f32_e32 v128, v155, v128
	v_add_f32_e32 v128, v156, v128
	v_exp_f32_e32 v195, v129
	v_add_f32_e32 v128, v157, v128
	v_exp_f32_e32 v196, v130
	v_add_f32_e32 v128, v158, v128
	v_exp_f32_e32 v197, v131
	v_add_f32_e32 v128, v159, v128
	v_exp_f32_e32 v214, v132
	v_add_f32_e32 v128, v194, v128
	v_exp_f32_e32 v215, v133
	v_add_f32_e32 v128, v195, v128
	v_exp_f32_e32 v216, v134
	v_add_f32_e32 v128, v196, v128
	v_exp_f32_e32 v217, v135
	v_add_f32_e32 v128, v197, v128
	v_exp_f32_e32 v220, v136
	v_add_f32_e32 v128, v214, v128
	v_exp_f32_e32 v221, v137
	v_add_f32_e32 v128, v215, v128
	v_exp_f32_e32 v222, v138
	v_add_f32_e32 v128, v216, v128
	v_exp_f32_e32 v223, v139
	v_add_f32_e32 v128, v217, v128
	v_exp_f32_e32 v231, v140
	v_add_f32_e32 v128, v220, v128
	v_exp_f32_e32 v232, v141
	v_add_f32_e32 v128, v221, v128
	v_exp_f32_e32 v233, v142
	v_add_f32_e32 v128, v222, v128
	v_exp_f32_e32 v143, v143
	v_add_f32_e32 v128, v223, v128
	v_add_f32_e32 v128, v231, v128
	v_add_f32_e32 v128, v232, v128
	v_add_f32_e32 v128, v233, v128
	v_add_f32_e32 v212, v143, v128
	v_mov_b32_e32 v230, v212
	v_cvt_pk_bf16_f32 v128, v144, v145
	v_cvt_pk_bf16_f32 v129, v146, v147
	v_cvt_pk_bf16_f32 v130, v148, v149
	v_cvt_pk_bf16_f32 v131, v150, v151
	v_cvt_pk_bf16_f32 v132, v152, v153
	v_cvt_pk_bf16_f32 v133, v154, v155
	v_cvt_pk_bf16_f32 v134, v156, v157
	v_cvt_pk_bf16_f32 v135, v158, v159
	v_cvt_pk_bf16_f32 v136, v194, v195
	v_cvt_pk_bf16_f32 v137, v196, v197
	v_cvt_pk_bf16_f32 v138, v214, v215
	v_cvt_pk_bf16_f32 v139, v216, v217
	v_cvt_pk_bf16_f32 v140, v220, v221
	v_cvt_pk_bf16_f32 v141, v222, v223
	v_cvt_pk_bf16_f32 v142, v231, v232
	v_cvt_pk_bf16_f32 v143, v233, v143
	s_nop 1
	v_permlane32_swap_b32_e32 v212, v230
	v_cmp_gt_f32_e32 vcc, 1.0, v229
	s_cbranch_vccnz .Lm1_resc

; #define SBAR() __builtin_amdgcn_sched_barrier(0)
; #define VF_WAIT(N) do { asm volatile("s_waitcnt lgkmcnt(" #N ")" ::: "memory"); SBAR(); } while (0)
; #define A_WAITBAR(N) asm volatile("s_waitcnt vmcnt(" #N ") lgkmcnt(0) ; A256BAR\n\ts_barrier" ::: "memory")
; __device__ __forceinline__ void pv8(f32x16* o, int vb, bf16x8 pa0, bf16x8 pa1, bf16x8 pa2, bf16x8 pa3) {
;   VFrag fa, fb; const int vb2 = vb + 16384;
;   vf_read<0>(fa, vb);
;   vf_read<1>(fb, vb);  VF_WAIT(8); vf_mma(o[0], fa, pa0, pa1, pa2, pa3); SBAR();
;   vf_read<2>(fa, vb);  VF_WAIT(8); vf_mma(o[1], fb, pa0, pa1, pa2, pa3); SBAR();
;   vf_read<3>(fb, vb);  VF_WAIT(8); vf_mma(o[2], fa, pa0, pa1, pa2, pa3); SBAR();
;   vf_read<0>(fa, vb2); VF_WAIT(8); vf_mma(o[3], fb, pa0, pa1, pa2, pa3); SBAR();
;   vf_read<1>(fb, vb2); VF_WAIT(8); vf_mma(o[4], fa, pa0, pa1, pa2, pa3); SBAR();
;   vf_read<2>(fa, vb2); VF_WAIT(8); vf_mma(o[5], fb, pa0, pa1, pa2, pa3); SBAR();
;   vf_read<3>(fb, vb2); VF_WAIT(8); vf_mma(o[6], fa, pa0, pa1, pa2, pa3); SBAR();
;   VF_WAIT(0); vf_mma(o[7], fb, pa0, pa1, pa2, pa3);
; }
; template <int mode> ...
;     ...
;     if (more) A_WAITBAR(6); else A_WAITBAR(0);
.Lp1_nodma:
	s_waitcnt lgkmcnt(8)
	v_mfma_f32_32x32x16_bf16 v[32:47], v[128:131], v[194:197], v[32:47]
	v_mfma_f32_32x32x16_bf16 v[32:47], v[132:135], v[214:217], v[32:47]
	v_mfma_f32_32x32x16_bf16 v[32:47], v[136:139], v[220:223], v[32:47]
	v_mfma_f32_32x32x16_bf16 v[32:47], v[140:143], v[232:235], v[32:47]
	ds_read_b64_tr_b16 v[194:195], v231 offset:0x600
	ds_read_b64_tr_b16 v[196:197], v231 offset:0xe00
	ds_read_b64_tr_b16 v[214:215], v231 offset:0x1600
	ds_read_b64_tr_b16 v[216:217], v231 offset:0x1e00
	ds_read_b64_tr_b16 v[220:221], v231 offset:0x2600
	ds_read_b64_tr_b16 v[222:223], v231 offset:0x2e00
	ds_read_b64_tr_b16 v[232:233], v231 offset:0x3600
	ds_read_b64_tr_b16 v[234:235], v231 offset:0x3e00
	s_waitcnt lgkmcnt(8)
	v_mfma_f32_32x32x16_bf16 v[96:111], v[128:131], v[144:147], v[96:111]
	v_mfma_f32_32x32x16_bf16 v[96:111], v[132:135], v[148:151], v[96:111]
	v_mfma_f32_32x32x16_bf16 v[96:111], v[136:139], v[152:155], v[96:111]
	v_mfma_f32_32x32x16_bf16 v[96:111], v[140:143], v[156:159], v[96:111]
	ds_read_b64_tr_b16 v[144:145], v236 offset:0
	ds_read_b64_tr_b16 v[146:147], v236 offset:0x800
	ds_read_b64_tr_b16 v[148:149], v236 offset:0x1000
	ds_read_b64_tr_b16 v[150:151], v236 offset:0x1800
	ds_read_b64_tr_b16 v[152:153], v236 offset:0x2000
	ds_read_b64_tr_b16 v[154:155], v236 offset:0x2800
	ds_read_b64_tr_b16 v[156:157], v236 offset:0x3000
	ds_read_b64_tr_b16 v[158:159], v236 offset:0x3800
	s_waitcnt lgkmcnt(8)
	v_mfma_f32_32x32x16_bf16 v[112:127], v[128:131], v[194:197], v[112:127]
	v_mfma_f32_32x32x16_bf16 v[112:127], v[132:135], v[214:217], v[112:127]
	v_mfma_f32_32x32x16_bf16 v[112:127], v[136:139], v[220:223], v[112:127]
	v_mfma_f32_32x32x16_bf16 v[112:127], v[140:143], v[232:235], v[112:127]
	ds_read_b64_tr_b16 v[194:195], v236 offset:0x200
	ds_read_b64_tr_b16 v[196:197], v236 offset:0xa00
	ds_read_b64_tr_b16 v[214:215], v236 offset:0x1200
	ds_read_b64_tr_b16 v[216:217], v236 offset:0x1a00
	ds_read_b64_tr_b16 v[220:221], v236 offset:0x2200
	ds_read_b64_tr_b16 v[222:223], v236 offset:0x2a00
	ds_read_b64_tr_b16 v[232:233], v236 offset:0x3200
	ds_read_b64_tr_b16 v[234:235], v236 offset:0x3a00
	s_waitcnt lgkmcnt(8)
	v_mfma_f32_32x32x16_bf16 v[64:79], v[128:131], v[144:147], v[64:79]
	v_mfma_f32_32x32x16_bf16 v[64:79], v[132:135], v[148:151], v[64:79]
	v_mfma_f32_32x32x16_bf16 v[64:79], v[136:139], v[152:155], v[64:79]
	v_mfma_f32_32x32x16_bf16 v[64:79], v[140:143], v[156:159], v[64:79]
	ds_read_b64_tr_b16 v[144:145], v236 offset:0x400
	ds_read_b64_tr_b16 v[146:147], v236 offset:0xc00
	ds_read_b64_tr_b16 v[148:149], v236 offset:0x1400
	ds_read_b64_tr_b16 v[150:151], v236 offset:0x1c00
	ds_read_b64_tr_b16 v[152:153], v236 offset:0x2400
	ds_read_b64_tr_b16 v[154:155], v236 offset:0x2c00
	ds_read_b64_tr_b16 v[156:157], v236 offset:0x3400
	ds_read_b64_tr_b16 v[158:159], v236 offset:0x3c00
	s_waitcnt lgkmcnt(8)
	v_mfma_f32_32x32x16_bf16 v[48:63], v[128:131], v[194:197], v[48:63]
	v_mfma_f32_32x32x16_bf16 v[48:63], v[132:135], v[214:217], v[48:63]
	v_mfma_f32_32x32x16_bf16 v[48:63], v[136:139], v[220:223], v[48:63]
	v_mfma_f32_32x32x16_bf16 v[48:63], v[140:143], v[232:235], v[48:63]
	ds_read_b64_tr_b16 v[194:195], v236 offset:0x600
	ds_read_b64_tr_b16 v[196:197], v236 offset:0xe00
	ds_read_b64_tr_b16 v[214:215], v236 offset:0x1600
	ds_read_b64_tr_b16 v[216:217], v236 offset:0x1e00
	ds_read_b64_tr_b16 v[220:221], v236 offset:0x2600
	ds_read_b64_tr_b16 v[222:223], v236 offset:0x2e00
	ds_read_b64_tr_b16 v[232:233], v236 offset:0x3600
	ds_read_b64_tr_b16 v[234:235], v236 offset:0x3e00
	s_waitcnt lgkmcnt(8)
	v_mfma_f32_32x32x16_bf16 v[0:15], v[128:131], v[144:147], v[0:15]
	v_mfma_f32_32x32x16_bf16 v[0:15], v[132:135], v[148:151], v[0:15]
	v_mfma_f32_32x32x16_bf16 v[0:15], v[136:139], v[152:155], v[0:15]
	v_mfma_f32_32x32x16_bf16 v[0:15], v[140:143], v[156:159], v[0:15]
	s_waitcnt lgkmcnt(0)
	v_mfma_f32_32x32x16_bf16 v[80:95], v[128:131], v[194:197], v[80:95]
	s_and_b64 vcc, exec, s[50:51]
	v_mfma_f32_32x32x16_bf16 v[80:95], v[132:135], v[214:217], v[80:95]
	v_mfma_f32_32x32x16_bf16 v[80:95], v[136:139], v[220:223], v[80:95]
	v_mfma_f32_32x32x16_bf16 v[80:95], v[140:143], v[232:235], v[80:95]
	s_cbranch_vccnz .Lm1_ybar0
	s_waitcnt vmcnt(6) lgkmcnt(0)
	s_barrier

; __device__ __forceinline__ float softmax_rel(f32x16& p0, f32x16& p1, bool first, float& m_reg, float& l_reg, bf16x8& pa0, bf16x8& pa1, bf16x8& pa2, bf16x8& pa3) {
;     ...
;   if (__builtin_expect(first || __any(pmax > THR2), 0)) {
;     const float dl = first ? pmax : fmaxf(pmax, 0.f);
;     m_reg += dl; alpha = first ? 1.f : __builtin_amdgcn_exp2f(-dl);
.Lm1_rare:
	s_mov_b64 s[24:25], 0
	s_mov_b64 s[62:63], 0
	s_branch .LBB0_405

; __device__ __forceinline__ float softmax_rel(f32x16& p0, f32x16& p1, bool first, float& m_reg, float& l_reg, bf16x8& pa0, bf16x8& pa1, bf16x8& pa2, bf16x8& pa3) {
;     ...
;   if (__builtin_expect(first || __any(pmax > THR2), 0)) {
;     const float dl = first ? pmax : fmaxf(pmax, 0.f);
;     m_reg += dl; alpha = first ? 1.f : __builtin_amdgcn_exp2f(-dl);
; #pragma unroll
;     for (int r = 0; r < 16; ++r) { p0[r] -= dl; p1[r] -= dl; }
;   }
.LBB0_387:
	v_exp_f32_e64 v194, -v212
	v_add_f32_e32 v227, v227, v212
	v_pk_add_f32 v[144:145], v[144:145], v[212:213] op_sel_hi:[1,0] neg_lo:[0,1] neg_hi:[0,1]
	v_pk_add_f32 v[128:129], v[128:129], v[212:213] op_sel_hi:[1,0] neg_lo:[0,1] neg_hi:[0,1]
	v_pk_add_f32 v[146:147], v[146:147], v[212:213] op_sel_hi:[1,0] neg_lo:[0,1] neg_hi:[0,1]
	v_pk_add_f32 v[130:131], v[130:131], v[212:213] op_sel_hi:[1,0] neg_lo:[0,1] neg_hi:[0,1]
	v_pk_add_f32 v[148:149], v[148:149], v[212:213] op_sel_hi:[1,0] neg_lo:[0,1] neg_hi:[0,1]
	v_pk_add_f32 v[132:133], v[132:133], v[212:213] op_sel_hi:[1,0] neg_lo:[0,1] neg_hi:[0,1]
	v_pk_add_f32 v[150:151], v[150:151], v[212:213] op_sel_hi:[1,0] neg_lo:[0,1] neg_hi:[0,1]
	v_pk_add_f32 v[134:135], v[134:135], v[212:213] op_sel_hi:[1,0] neg_lo:[0,1] neg_hi:[0,1]
	v_pk_add_f32 v[152:153], v[152:153], v[212:213] op_sel_hi:[1,0] neg_lo:[0,1] neg_hi:[0,1]
	v_pk_add_f32 v[136:137], v[136:137], v[212:213] op_sel_hi:[1,0] neg_lo:[0,1] neg_hi:[0,1]
	v_pk_add_f32 v[154:155], v[154:155], v[212:213] op_sel_hi:[1,0] neg_lo:[0,1] neg_hi:[0,1]
	v_pk_add_f32 v[138:139], v[138:139], v[212:213] op_sel_hi:[1,0] neg_lo:[0,1] neg_hi:[0,1]
	v_pk_add_f32 v[156:157], v[156:157], v[212:213] op_sel_hi:[1,0] neg_lo:[0,1] neg_hi:[0,1]
	v_pk_add_f32 v[140:141], v[140:141], v[212:213] op_sel_hi:[1,0] neg_lo:[0,1] neg_hi:[0,1]
	v_pk_add_f32 v[158:159], v[158:159], v[212:213] op_sel_hi:[1,0] neg_lo:[0,1] neg_hi:[0,1]
	v_pk_add_f32 v[142:143], v[142:143], v[212:213] op_sel_hi:[1,0] neg_lo:[0,1] neg_hi:[0,1]
	v_cndmask_b32_e64 v229, v194, 1.0, s[56:57]
	s_branch .LBB0_388
.Lm1_resc:
	s_and_saveexec_b64 s[24:25], s[40:41]
	ds_write_b32 v224, v229 offset:128
	s_or_b64 exec, exec, s[24:25]
	s_waitcnt lgkmcnt(0)
	v_add_u32_e32 v144, s6, v198
	ds_read_b128 v[156:159], v144 offset:224
	ds_read_b128 v[152:155], v144 offset:192
	ds_read_b128 v[148:151], v144 offset:160
	ds_read_b128 v[144:147], v144 offset:128
	s_waitcnt lgkmcnt(3)
	v_pk_mul_f32 v[28:29], v[28:29], v[156:157]
	s_waitcnt lgkmcnt(2)
	v_pk_mul_f32 v[24:25], v[24:25], v[152:153]
	s_waitcnt lgkmcnt(1)
	v_pk_mul_f32 v[20:21], v[20:21], v[148:149]
	v_pk_mul_f32 v[30:31], v[30:31], v[158:159]
	v_pk_mul_f32 v[26:27], v[26:27], v[154:155]
	v_pk_mul_f32 v[22:23], v[22:23], v[150:151]
	s_waitcnt lgkmcnt(0)
	v_pk_mul_f32 v[18:19], v[18:19], v[146:147]
	v_pk_mul_f32 v[16:17], v[16:17], v[144:145]
	v_pk_mul_f32 v[44:45], v[44:45], v[156:157]
	v_pk_mul_f32 v[40:41], v[40:41], v[152:153]
	v_pk_mul_f32 v[36:37], v[36:37], v[148:149]
	v_pk_mul_f32 v[46:47], v[46:47], v[158:159]
	v_pk_mul_f32 v[42:43], v[42:43], v[154:155]
	v_pk_mul_f32 v[38:39], v[38:39], v[150:151]
	v_pk_mul_f32 v[34:35], v[34:35], v[146:147]
	v_pk_mul_f32 v[32:33], v[32:33], v[144:145]
	v_pk_mul_f32 v[108:109], v[108:109], v[156:157]
	v_pk_mul_f32 v[104:105], v[104:105], v[152:153]
	v_pk_mul_f32 v[100:101], v[100:101], v[148:149]
	v_pk_mul_f32 v[110:111], v[110:111], v[158:159]
	v_pk_mul_f32 v[106:107], v[106:107], v[154:155]
	v_pk_mul_f32 v[102:103], v[102:103], v[150:151]
	v_pk_mul_f32 v[98:99], v[98:99], v[146:147]
	v_pk_mul_f32 v[96:97], v[96:97], v[144:145]
	v_pk_mul_f32 v[124:125], v[124:125], v[156:157]
	v_pk_mul_f32 v[120:121], v[120:121], v[152:153]
	v_pk_mul_f32 v[116:117], v[116:117], v[148:149]
	v_pk_mul_f32 v[126:127], v[126:127], v[158:159]
	v_pk_mul_f32 v[122:123], v[122:123], v[154:155]
	v_pk_mul_f32 v[118:119], v[118:119], v[150:151]
	v_pk_mul_f32 v[114:115], v[114:115], v[146:147]
	v_pk_mul_f32 v[112:113], v[112:113], v[144:145]
	v_pk_mul_f32 v[76:77], v[76:77], v[156:157]
	v_pk_mul_f32 v[72:73], v[72:73], v[152:153]
	v_pk_mul_f32 v[68:69], v[68:69], v[148:149]
	v_pk_mul_f32 v[78:79], v[78:79], v[158:159]
	v_pk_mul_f32 v[74:75], v[74:75], v[154:155]
	v_pk_mul_f32 v[70:71], v[70:71], v[150:151]
	v_pk_mul_f32 v[66:67], v[66:67], v[146:147]
	v_pk_mul_f32 v[64:65], v[64:65], v[144:145]
	v_pk_mul_f32 v[60:61], v[60:61], v[156:157]
	v_pk_mul_f32 v[56:57], v[56:57], v[152:153]
	v_pk_mul_f32 v[52:53], v[52:53], v[148:149]
	v_pk_mul_f32 v[62:63], v[62:63], v[158:159]
	v_pk_mul_f32 v[58:59], v[58:59], v[154:155]
	v_pk_mul_f32 v[54:55], v[54:55], v[150:151]
	v_pk_mul_f32 v[50:51], v[50:51], v[146:147]
	v_pk_mul_f32 v[48:49], v[48:49], v[144:145]
	v_pk_mul_f32 v[12:13], v[12:13], v[156:157]
	v_pk_mul_f32 v[8:9], v[8:9], v[152:153]
	v_pk_mul_f32 v[4:5], v[4:5], v[148:149]
	v_pk_mul_f32 v[14:15], v[14:15], v[158:159]
	v_pk_mul_f32 v[10:11], v[10:11], v[154:155]
	v_pk_mul_f32 v[6:7], v[6:7], v[150:151]
	v_pk_mul_f32 v[2:3], v[2:3], v[146:147]
	v_pk_mul_f32 v[0:1], v[0:1], v[144:145]
	v_pk_mul_f32 v[92:93], v[92:93], v[156:157]
	v_pk_mul_f32 v[88:89], v[88:89], v[152:153]
	v_pk_mul_f32 v[84:85], v[84:85], v[148:149]
	v_pk_mul_f32 v[94:95], v[94:95], v[158:159]
	v_pk_mul_f32 v[90:91], v[90:91], v[154:155]
	v_pk_mul_f32 v[86:87], v[86:87], v[150:151]
	v_pk_mul_f32 v[82:83], v[82:83], v[146:147]
	v_pk_mul_f32 v[80:81], v[80:81], v[144:145]
	s_branch .LBB0_392
